# compress K loop: the two 64-B halves of each W1t cache line (k-step pair) loaded back to back, so each line is fetched once; hoisted bias/W2t/k_gain loads
# baseline (speedup 1.0000x reference)
; DI unsigned pk2(float lo, float hi) { f32x2 v = {lo, hi}; bf16x2n b = __builtin_convertvector(v, bf16x2n); return __builtin_bit_cast(unsigned, b); }
; DI void prep_phase(const int wv, const Params& p, int l, LAS unsigned char* lds) {
;     ...
;             if (kv == 0) {
;                 float ss[4];
; #pragma unroll
;                 for (int i = 0; i < 4; ++i) { float s = acc2[i] * acc2[i]; s += __shfl_xor(s, 1); s += __shfl_xor(s, 2); s += __shfl_xor(s, 4); s += __shfl_xor(s, 8); ss[i] = s; }
;                 if (r16 == 0) {
; #pragma unroll
;                     for (int i = 0; i < 4; ++i) red[wave * 16 + 4 * kq + i] = ss[i]; }
;                 __syncthreads();
;                 const float gn = p.k_gain[(l * 3 + 0) * 128 + n];
; #pragma unroll
;                 for (int i = 0; i < 4; ++i) { const int row = 4 * kq + i; float s = 0.f;
; #pragma unroll
;                     for (int w = 0; w < 8; ++w) s += red[w * 16 + row];
;                     const float rstd = rsqrtf(s * (1.f / 128.f) + 1e-6f); const int c = c0 + row;
;                     const float v = (c < 255) ? acc2[i] * rstd * gn : 0.f;
;                     kcmp[(((size_t)b * 2 + g) * 256 + c) * 128 + n] = (bf16_t)(pk2(v, 0.f) & 0xffffu); }
.LBB0_359:
	s_or_b64 exec, exec, s[6:7]
	s_waitcnt lgkmcnt(0)
	s_barrier
	v_mov_b32_e32 v52, v116
	s_lshl_b32 s1, s16, 9
	s_or_b32 s6, s1, s0
	v_or_b32_e32 v4, s6, v12
	v_lshlrev_b32_e32 v4, 8, v4
	v_mov_b32_e32 v5, v161
	v_lshl_add_u64 v[50:51], v[40:41], 0, v[4:5]
	ds_read_b128 v[4:7], v74 offset:8192
	ds_read_b128 v[8:11], v74 offset:8256
	ds_read_b128 v[12:15], v74 offset:8320
	ds_read_b128 v[16:19], v74 offset:8384
	ds_read_b128 v[20:23], v74 offset:8448
	ds_read_b128 v[24:27], v74 offset:8512
	s_waitcnt lgkmcnt(5)
	v_pk_add_f32 v[4:5], v[4:5], 0 op_sel_hi:[1,0]
	ds_read_b128 v[28:31], v74 offset:8576
	ds_read_b128 v[46:49], v74 offset:8640
	s_waitcnt lgkmcnt(6)
	v_pk_add_f32 v[4:5], v[4:5], v[8:9]
	s_mov_b32 s0, 0x358637bd
	s_waitcnt lgkmcnt(5)
	v_pk_add_f32 v[4:5], v[4:5], v[12:13]
	v_mov_b64_e32 v[8:9], s[0:1]
	s_waitcnt lgkmcnt(4)
	v_pk_add_f32 v[4:5], v[4:5], v[16:17]
	s_brev_b32 s8, 60
	s_waitcnt lgkmcnt(3)
	v_pk_add_f32 v[4:5], v[4:5], v[20:21]
	s_mov_b32 s7, 0x800000
	s_waitcnt lgkmcnt(2)
	v_pk_add_f32 v[4:5], v[4:5], v[24:25]
	s_waitcnt lgkmcnt(1)
	v_pk_add_f32 v[4:5], v[4:5], v[28:29]
	s_waitcnt lgkmcnt(0)
	v_pk_add_f32 v[4:5], v[4:5], v[46:47]
	s_nop 0
	v_pk_fma_f32 v[4:5], v[4:5], s[8:9], v[8:9] op_sel_hi:[1,0,0]
	s_nop 0
	v_mul_f32_e32 v12, 0x4b800000, v4
	v_cmp_gt_f32_e64 s[0:1], s7, v4
	v_cmp_gt_f32_e32 vcc, s7, v5
	s_nop 0
	v_cndmask_b32_e64 v4, v4, v12, s[0:1]
	v_rsq_f32_e32 v4, v4
	s_nop 0
	v_mul_f32_e32 v12, 0x45800000, v4
	v_cndmask_b32_e64 v4, v4, v12, s[0:1]
	v_mul_f32_e32 v0, v0, v4
	s_waitcnt vmcnt(0)
	v_mul_f32_e32 v0, v52, v0
	v_cvt_pk_bf16_f32 v0, v0, s0
	global_store_short v[50:51], v0, off
	v_mul_f32_e32 v0, 0x4b800000, v5
	v_cndmask_b32_e32 v0, v5, v0, vcc
	v_rsq_f32_e32 v0, v0
	s_nop 0
	v_mul_f32_e32 v4, 0x45800000, v0
	v_cndmask_b32_e32 v0, v0, v4, vcc
	v_mul_f32_e32 v0, v1, v0
	v_or_b32_e32 v4, s15, v75
	v_mul_f32_e32 v0, v52, v0
	v_cvt_pk_bf16_f32 v5, v0, s0
	v_or_b32_e32 v0, s6, v4
	v_lshlrev_b32_e32 v0, 8, v0
	v_mov_b32_e32 v1, v161
	v_lshl_add_u64 v[0:1], v[40:41], 0, v[0:1]
	global_store_short v[0:1], v5, off
	v_pk_add_f32 v[4:5], v[6:7], 0 op_sel_hi:[1,0]
	v_or_b32_e32 v0, s15, v76
	v_pk_add_f32 v[4:5], v[4:5], v[10:11]
	v_or_b32_e32 v0, s6, v0
	v_pk_add_f32 v[4:5], v[4:5], v[14:15]
	v_lshlrev_b32_e32 v0, 8, v0
	v_pk_add_f32 v[4:5], v[4:5], v[18:19]
	v_mov_b32_e32 v1, v161
	v_pk_add_f32 v[4:5], v[4:5], v[22:23]
	v_lshl_add_u64 v[0:1], v[40:41], 0, v[0:1]
	v_pk_add_f32 v[4:5], v[4:5], v[26:27]
	s_nop 0
	v_pk_add_f32 v[4:5], v[4:5], v[30:31]
	s_nop 0
	v_pk_add_f32 v[4:5], v[4:5], v[48:49]
	s_nop 0
	v_pk_fma_f32 v[4:5], v[4:5], s[8:9], v[8:9] op_sel_hi:[1,0,0]
	s_nop 0
	v_mul_f32_e32 v6, 0x4b800000, v4
	v_cmp_gt_f32_e64 s[0:1], s7, v4
	v_cmp_gt_f32_e32 vcc, s7, v5
	s_nop 0
	v_cndmask_b32_e64 v4, v4, v6, s[0:1]
	v_rsq_f32_e32 v4, v4
	s_nop 0
	v_mul_f32_e32 v6, 0x45800000, v4
	v_cndmask_b32_e64 v4, v4, v6, s[0:1]
	v_mul_f32_e32 v2, v2, v4
	v_mul_f32_e32 v2, v52, v2
	v_cvt_pk_bf16_f32 v2, v2, s0
	global_store_short v[0:1], v2, off
	v_mul_f32_e32 v0, 0x4b800000, v5
	v_cndmask_b32_e32 v0, v5, v0, vcc
	v_rsq_f32_e32 v0, v0
	s_nop 0
	v_mul_f32_e32 v1, 0x45800000, v0
	v_cndmask_b32_e32 v0, v0, v1, vcc
	v_mul_f32_e32 v0, v3, v0
	v_or_b32_e32 v1, s15, v77
	v_mul_f32_e32 v0, v52, v0
	v_cvt_pk_bf16_f32 v0, v0, s0
	v_cmp_ne_u32_e32 vcc, s69, v1
	s_nop 1
	v_cndmask_b32_e32 v2, 0, v0, vcc
	v_or_b32_e32 v0, s6, v1
	v_lshlrev_b32_e32 v0, 8, v0
	v_mov_b32_e32 v1, v161
	v_lshl_add_u64 v[0:1], v[40:41], 0, v[0:1]
	global_store_short v[0:1], v2, off

; DI void prep_phase(const int wv, const Params& p, int l, LAS unsigned char* lds) {
;     ...
; #pragma unroll 2
;             for (int kk = 0; kk < 16; ++kk) { const int ks = 16 * wave + kk;
;                 const bf16x8 a = *(const bf16x8*)(Arow + (size_t)(ks >> 2) * PWID + (ks & 3) * 32);
; #pragma unroll
;                 for (int nt = 0; nt < 8; ++nt) { const bf16x8 bb = *(const bf16x8*)(Brow + (size_t)nt * 16 * 4096 + ks * 32);
;                     acc[nt] = __builtin_amdgcn_mfma_f32_16x16x32_bf16(a, bb, acc[nt], 0, 0, 0); }
;             }
.LBB0_362:
	s_sub_i32 s17, s1, 32
	v_ashrrev_i32_e32 v50, 2, v80
	s_and_b32 s17, s17, 64
	v_mad_i64_i32 v[50:51], s[18:19], v50, s68, v[46:47]
	s_lshl_b32 s86, s17, 1
	v_lshl_add_u64 v[50:51], v[50:51], 0, s[86:87]
	global_load_dwordx4 v[82:85], v[50:51], off
	v_add_u32_e32 v81, 1, v80
	v_ashrrev_i32_e32 v81, 2, v81
	s_and_b32 s17, s1, 0x60
	s_lshl_b32 s86, s17, 1
	v_mad_i64_i32 v[52:53], s[18:19], v81, s68, v[46:47]
	v_lshl_add_u64 v[52:53], v[52:53], 0, s[86:87]
	global_load_dwordx4 v[86:89], v[52:53], off
	v_add_u32_e32 v80, 2, v80
	v_lshl_add_u64 v[90:91], v[48:49], 0, s[12:13]
	s_mov_b32 s17, 0x5b00000
	v_add_co_u32_e32 v54, vcc, s17, v90
	s_mov_b32 s17, 0x5b20000
	s_nop 0
	v_addc_co_u32_e32 v55, vcc, 0, v91, vcc
	v_add_co_u32_e32 v56, vcc, s17, v90
	s_mov_b32 s17, 0x5b40000
	s_nop 0
	v_addc_co_u32_e32 v57, vcc, 0, v91, vcc
	v_add_co_u32_e32 v58, vcc, s17, v90
	s_mov_b32 s17, 0x5b60000
	s_nop 0
	v_addc_co_u32_e32 v59, vcc, 0, v91, vcc
	v_add_co_u32_e32 v60, vcc, s17, v90
	s_mov_b32 s17, 0x5b80000
	s_nop 0
	v_addc_co_u32_e32 v61, vcc, 0, v91, vcc
	v_add_co_u32_e32 v62, vcc, s17, v90
	s_mov_b32 s17, 0x5ba0000
	s_nop 0
	v_addc_co_u32_e32 v63, vcc, 0, v91, vcc
	v_add_co_u32_e32 v64, vcc, s17, v90
	s_mov_b32 s17, 0x5bc0000
	s_nop 0
	v_addc_co_u32_e32 v65, vcc, 0, v91, vcc
	v_add_co_u32_e32 v156, vcc, s17, v90
	s_mov_b32 s17, 0x5be0000
	s_nop 0
	v_addc_co_u32_e32 v157, vcc, 0, v91, vcc
	v_add_co_u32_e32 v158, vcc, s17, v90
	s_mov_b32 s17, 0x5c00000
	s_nop 0
	v_addc_co_u32_e32 v159, vcc, 0, v91, vcc
	global_load_dwordx4 v[92:95], v[54:55], off
	global_load_dwordx4 v[124:127], v[54:55], off offset:64
	global_load_dwordx4 v[96:99], v[56:57], off
	global_load_dwordx4 v[128:131], v[56:57], off offset:64
	global_load_dwordx4 v[100:103], v[58:59], off
	global_load_dwordx4 v[132:135], v[58:59], off offset:64
	global_load_dwordx4 v[104:107], v[60:61], off
	global_load_dwordx4 v[136:139], v[60:61], off offset:64
	global_load_dwordx4 v[108:111], v[62:63], off
	global_load_dwordx4 v[140:143], v[62:63], off offset:64
	global_load_dwordx4 v[112:115], v[64:65], off
	global_load_dwordx4 v[144:147], v[64:65], off offset:64
	global_load_dwordx4 v[116:119], v[156:157], off
	global_load_dwordx4 v[148:151], v[156:157], off offset:64
	global_load_dwordx4 v[120:123], v[158:159], off
	global_load_dwordx4 v[152:155], v[158:159], off offset:64
	s_add_u32 s12, s12, 0x80
	s_addc_u32 s13, s13, 0
	s_add_i32 s1, s1, 64
	s_sub_i32 s17, s1, 32
	v_ashrrev_i32_e32 v50, 2, v80
	s_and_b32 s17, s17, 64
	v_mad_i64_i32 v[50:51], s[18:19], v50, s68, v[46:47]
	s_lshl_b32 s86, s17, 1
	v_lshl_add_u64 v[50:51], v[50:51], 0, s[86:87]
	global_load_dwordx4 v[162:165], v[50:51], off
	v_add_u32_e32 v81, 1, v80
	v_ashrrev_i32_e32 v81, 2, v81
	s_and_b32 s17, s1, 0x60
	s_lshl_b32 s86, s17, 1
	v_mad_i64_i32 v[52:53], s[18:19], v81, s68, v[46:47]
	v_lshl_add_u64 v[52:53], v[52:53], 0, s[86:87]
	global_load_dwordx4 v[168:171], v[52:53], off
	v_add_u32_e32 v80, 2, v80
	v_lshl_add_u64 v[90:91], v[48:49], 0, s[12:13]
	s_mov_b32 s17, 0x5b00000
	v_add_co_u32_e32 v54, vcc, s17, v90
	s_mov_b32 s17, 0x5b20000
	s_nop 0
	v_addc_co_u32_e32 v55, vcc, 0, v91, vcc
	v_add_co_u32_e32 v56, vcc, s17, v90
	s_mov_b32 s17, 0x5b40000
	s_nop 0
	v_addc_co_u32_e32 v57, vcc, 0, v91, vcc
	v_add_co_u32_e32 v58, vcc, s17, v90
	s_mov_b32 s17, 0x5b60000
	s_nop 0
	v_addc_co_u32_e32 v59, vcc, 0, v91, vcc
	v_add_co_u32_e32 v60, vcc, s17, v90
	s_mov_b32 s17, 0x5b80000
	s_nop 0
	v_addc_co_u32_e32 v61, vcc, 0, v91, vcc
	v_add_co_u32_e32 v62, vcc, s17, v90
	s_mov_b32 s17, 0x5ba0000
	s_nop 0
	v_addc_co_u32_e32 v63, vcc, 0, v91, vcc
	v_add_co_u32_e32 v64, vcc, s17, v90
	s_mov_b32 s17, 0x5bc0000
	s_nop 0
	v_addc_co_u32_e32 v65, vcc, 0, v91, vcc
	v_add_co_u32_e32 v156, vcc, s17, v90
	s_mov_b32 s17, 0x5be0000
	s_nop 0
	v_addc_co_u32_e32 v157, vcc, 0, v91, vcc
	v_add_co_u32_e32 v158, vcc, s17, v90
	s_mov_b32 s17, 0x5c00000
	s_nop 0
	v_addc_co_u32_e32 v159, vcc, 0, v91, vcc
	global_load_dwordx4 v[172:175], v[54:55], off
	global_load_dwordx4 v[214:217], v[54:55], off offset:64
	global_load_dwordx4 v[176:179], v[56:57], off
	global_load_dwordx4 v[218:221], v[56:57], off offset:64
	global_load_dwordx4 v[180:183], v[58:59], off
	global_load_dwordx4 v[222:225], v[58:59], off offset:64
	global_load_dwordx4 v[184:187], v[60:61], off
	global_load_dwordx4 v[226:229], v[60:61], off offset:64
	global_load_dwordx4 v[188:191], v[62:63], off
	global_load_dwordx4 v[230:233], v[62:63], off offset:64
	global_load_dwordx4 v[192:195], v[64:65], off
	global_load_dwordx4 v[234:237], v[64:65], off offset:64
	global_load_dwordx4 v[196:199], v[156:157], off
	global_load_dwordx4 v[238:241], v[156:157], off offset:64
	global_load_dwordx4 v[210:213], v[158:159], off
	global_load_dwordx4 v[242:245], v[158:159], off offset:64
	s_add_u32 s12, s12, 0x80
	s_addc_u32 s13, s13, 0
	s_add_i32 s1, s1, 64
	s_waitcnt vmcnt(33)
	v_mfma_f32_16x16x32_bf16 v[16:19], v[82:85], v[92:95], v[16:19]
	s_waitcnt vmcnt(32)
	v_mfma_f32_16x16x32_bf16 v[16:19], v[86:89], v[124:127], v[16:19]
	s_waitcnt vmcnt(31)
	v_mfma_f32_16x16x32_bf16 v[20:23], v[82:85], v[96:99], v[20:23]
	s_waitcnt vmcnt(30)
	v_mfma_f32_16x16x32_bf16 v[20:23], v[86:89], v[128:131], v[20:23]
	s_waitcnt vmcnt(29)
	v_mfma_f32_16x16x32_bf16 v[12:15], v[82:85], v[100:103], v[12:15]
	s_waitcnt vmcnt(28)
	v_mfma_f32_16x16x32_bf16 v[12:15], v[86:89], v[132:135], v[12:15]
	s_waitcnt vmcnt(27)
	v_mfma_f32_16x16x32_bf16 v[8:11], v[82:85], v[104:107], v[8:11]
	s_waitcnt vmcnt(26)
	v_mfma_f32_16x16x32_bf16 v[8:11], v[86:89], v[136:139], v[8:11]
	s_waitcnt vmcnt(25)
	v_mfma_f32_16x16x32_bf16 v[24:27], v[82:85], v[108:111], v[24:27]
	s_waitcnt vmcnt(24)
; DI void prep_phase(const int wv, const Params& p, int l, LAS unsigned char* lds) {
;     ...
; #pragma unroll 2
;             for (int kk = 0; kk < 16; ++kk) { const int ks = 16 * wave + kk;
;                 const bf16x8 a = *(const bf16x8*)(Arow + (size_t)(ks >> 2) * PWID + (ks & 3) * 32);
; #pragma unroll
;                 for (int nt = 0; nt < 8; ++nt) { const bf16x8 bb = *(const bf16x8*)(Brow + (size_t)nt * 16 * 4096 + ks * 32);
;                     acc[nt] = __builtin_amdgcn_mfma_f32_16x16x32_bf16(a, bb, acc[nt], 0, 0, 0); }
;             }
	v_mfma_f32_16x16x32_bf16 v[24:27], v[86:89], v[140:143], v[24:27]
	s_waitcnt vmcnt(23)
	v_mfma_f32_16x16x32_bf16 v[28:31], v[82:85], v[112:115], v[28:31]
	s_waitcnt vmcnt(22)
	v_mfma_f32_16x16x32_bf16 v[28:31], v[86:89], v[144:147], v[28:31]
	s_waitcnt vmcnt(21)
	v_mfma_f32_16x16x32_bf16 v[0:3], v[82:85], v[116:119], v[0:3]
	s_waitcnt vmcnt(20)
	v_mfma_f32_16x16x32_bf16 v[0:3], v[86:89], v[148:151], v[0:3]
	s_waitcnt vmcnt(19)
	v_mfma_f32_16x16x32_bf16 v[4:7], v[82:85], v[120:123], v[4:7]
	s_waitcnt vmcnt(18)
	v_mfma_f32_16x16x32_bf16 v[4:7], v[86:89], v[152:155], v[4:7]
	s_sub_i32 s17, s1, 32
	v_ashrrev_i32_e32 v50, 2, v80
	s_and_b32 s17, s17, 64
	v_mad_i64_i32 v[50:51], s[18:19], v50, s68, v[46:47]
	s_lshl_b32 s86, s17, 1
	v_lshl_add_u64 v[50:51], v[50:51], 0, s[86:87]
	global_load_dwordx4 v[82:85], v[50:51], off
	v_add_u32_e32 v81, 1, v80
	v_ashrrev_i32_e32 v81, 2, v81
	s_and_b32 s17, s1, 0x60
	s_lshl_b32 s86, s17, 1
	v_mad_i64_i32 v[52:53], s[18:19], v81, s68, v[46:47]
	v_lshl_add_u64 v[52:53], v[52:53], 0, s[86:87]
	global_load_dwordx4 v[86:89], v[52:53], off
	v_add_u32_e32 v80, 2, v80
	v_lshl_add_u64 v[90:91], v[48:49], 0, s[12:13]
	s_mov_b32 s17, 0x5b00000
	v_add_co_u32_e32 v54, vcc, s17, v90
	s_mov_b32 s17, 0x5b20000
	s_nop 0
	v_addc_co_u32_e32 v55, vcc, 0, v91, vcc
	v_add_co_u32_e32 v56, vcc, s17, v90
	s_mov_b32 s17, 0x5b40000
	s_nop 0
	v_addc_co_u32_e32 v57, vcc, 0, v91, vcc
	v_add_co_u32_e32 v58, vcc, s17, v90
	s_mov_b32 s17, 0x5b60000
	s_nop 0
	v_addc_co_u32_e32 v59, vcc, 0, v91, vcc
	v_add_co_u32_e32 v60, vcc, s17, v90
	s_mov_b32 s17, 0x5b80000
	s_nop 0
	v_addc_co_u32_e32 v61, vcc, 0, v91, vcc
	v_add_co_u32_e32 v62, vcc, s17, v90
	s_mov_b32 s17, 0x5ba0000
	s_nop 0
	v_addc_co_u32_e32 v63, vcc, 0, v91, vcc
	v_add_co_u32_e32 v64, vcc, s17, v90
	s_mov_b32 s17, 0x5bc0000
	s_nop 0
	v_addc_co_u32_e32 v65, vcc, 0, v91, vcc
	v_add_co_u32_e32 v156, vcc, s17, v90
	s_mov_b32 s17, 0x5be0000
	s_nop 0
	v_addc_co_u32_e32 v157, vcc, 0, v91, vcc
	v_add_co_u32_e32 v158, vcc, s17, v90
	s_mov_b32 s17, 0x5c00000
	s_nop 0
	v_addc_co_u32_e32 v159, vcc, 0, v91, vcc
	global_load_dwordx4 v[92:95], v[54:55], off
	global_load_dwordx4 v[124:127], v[54:55], off offset:64
	global_load_dwordx4 v[96:99], v[56:57], off
	global_load_dwordx4 v[128:131], v[56:57], off offset:64
	global_load_dwordx4 v[100:103], v[58:59], off
	global_load_dwordx4 v[132:135], v[58:59], off offset:64
	global_load_dwordx4 v[104:107], v[60:61], off
	global_load_dwordx4 v[136:139], v[60:61], off offset:64
	global_load_dwordx4 v[108:111], v[62:63], off
	global_load_dwordx4 v[140:143], v[62:63], off offset:64
	global_load_dwordx4 v[112:115], v[64:65], off
	global_load_dwordx4 v[144:147], v[64:65], off offset:64
	global_load_dwordx4 v[116:119], v[156:157], off
	global_load_dwordx4 v[148:151], v[156:157], off offset:64
	global_load_dwordx4 v[120:123], v[158:159], off
	global_load_dwordx4 v[152:155], v[158:159], off offset:64
	s_add_u32 s12, s12, 0x80
	s_addc_u32 s13, s13, 0
	s_add_i32 s1, s1, 64
	s_waitcnt vmcnt(33)
	v_mfma_f32_16x16x32_bf16 v[16:19], v[162:165], v[172:175], v[16:19]
	s_waitcnt vmcnt(32)
	v_mfma_f32_16x16x32_bf16 v[16:19], v[168:171], v[214:217], v[16:19]
	s_waitcnt vmcnt(31)
	v_mfma_f32_16x16x32_bf16 v[20:23], v[162:165], v[176:179], v[20:23]
	s_waitcnt vmcnt(30)
	v_mfma_f32_16x16x32_bf16 v[20:23], v[168:171], v[218:221], v[20:23]
	s_waitcnt vmcnt(29)
	v_mfma_f32_16x16x32_bf16 v[12:15], v[162:165], v[180:183], v[12:15]
	s_waitcnt vmcnt(28)
	v_mfma_f32_16x16x32_bf16 v[12:15], v[168:171], v[222:225], v[12:15]
	s_waitcnt vmcnt(27)
	v_mfma_f32_16x16x32_bf16 v[8:11], v[162:165], v[184:187], v[8:11]
	s_waitcnt vmcnt(26)
	v_mfma_f32_16x16x32_bf16 v[8:11], v[168:171], v[226:229], v[8:11]
	s_waitcnt vmcnt(25)
	v_mfma_f32_16x16x32_bf16 v[24:27], v[162:165], v[188:191], v[24:27]
	s_waitcnt vmcnt(24)
	v_mfma_f32_16x16x32_bf16 v[24:27], v[168:171], v[230:233], v[24:27]
	s_waitcnt vmcnt(23)
	v_mfma_f32_16x16x32_bf16 v[28:31], v[162:165], v[192:195], v[28:31]
	s_waitcnt vmcnt(22)
	v_mfma_f32_16x16x32_bf16 v[28:31], v[168:171], v[234:237], v[28:31]
	s_waitcnt vmcnt(21)
	v_mfma_f32_16x16x32_bf16 v[0:3], v[162:165], v[196:199], v[0:3]
	s_waitcnt vmcnt(20)
	v_mfma_f32_16x16x32_bf16 v[0:3], v[168:171], v[238:241], v[0:3]
	s_waitcnt vmcnt(19)
	v_mfma_f32_16x16x32_bf16 v[4:7], v[162:165], v[210:213], v[4:7]
	s_waitcnt vmcnt(18)
	v_mfma_f32_16x16x32_bf16 v[4:7], v[168:171], v[242:245], v[4:7]
	s_sub_i32 s17, s1, 32
	v_ashrrev_i32_e32 v50, 2, v80
	s_and_b32 s17, s17, 64
	v_mad_i64_i32 v[50:51], s[18:19], v50, s68, v[46:47]
	s_lshl_b32 s86, s17, 1
	v_lshl_add_u64 v[50:51], v[50:51], 0, s[86:87]
	global_load_dwordx4 v[162:165], v[50:51], off
	v_add_u32_e32 v81, 1, v80
	v_ashrrev_i32_e32 v81, 2, v81
	s_and_b32 s17, s1, 0x60
	s_lshl_b32 s86, s17, 1
	v_mad_i64_i32 v[52:53], s[18:19], v81, s68, v[46:47]
	v_lshl_add_u64 v[52:53], v[52:53], 0, s[86:87]
	global_load_dwordx4 v[168:171], v[52:53], off
	v_add_u32_e32 v80, 2, v80
	v_lshl_add_u64 v[90:91], v[48:49], 0, s[12:13]
	s_mov_b32 s17, 0x5b00000
	v_add_co_u32_e32 v54, vcc, s17, v90
	s_mov_b32 s17, 0x5b20000
	s_nop 0
	v_addc_co_u32_e32 v55, vcc, 0, v91, vcc
	v_add_co_u32_e32 v56, vcc, s17, v90
	s_mov_b32 s17, 0x5b40000
	s_nop 0
	v_addc_co_u32_e32 v57, vcc, 0, v91, vcc
	v_add_co_u32_e32 v58, vcc, s17, v90
	s_mov_b32 s17, 0x5b60000
	s_nop 0
	v_addc_co_u32_e32 v59, vcc, 0, v91, vcc
	v_add_co_u32_e32 v60, vcc, s17, v90
	s_mov_b32 s17, 0x5b80000
	s_nop 0
	v_addc_co_u32_e32 v61, vcc, 0, v91, vcc
	v_add_co_u32_e32 v62, vcc, s17, v90
	s_mov_b32 s17, 0x5ba0000
	s_nop 0
	v_addc_co_u32_e32 v63, vcc, 0, v91, vcc
	v_add_co_u32_e32 v64, vcc, s17, v90
	s_mov_b32 s17, 0x5bc0000
	s_nop 0
	v_addc_co_u32_e32 v65, vcc, 0, v91, vcc
	v_add_co_u32_e32 v156, vcc, s17, v90
	s_mov_b32 s17, 0x5be0000
	s_nop 0
	v_addc_co_u32_e32 v157, vcc, 0, v91, vcc
	v_add_co_u32_e32 v158, vcc, s17, v90
	s_mov_b32 s17, 0x5c00000
	s_nop 0
	v_addc_co_u32_e32 v159, vcc, 0, v91, vcc
	global_load_dwordx4 v[172:175], v[54:55], off
	global_load_dwordx4 v[214:217], v[54:55], off offset:64
	global_load_dwordx4 v[176:179], v[56:57], off
	global_load_dwordx4 v[218:221], v[56:57], off offset:64
	global_load_dwordx4 v[180:183], v[58:59], off
	global_load_dwordx4 v[222:225], v[58:59], off offset:64
	global_load_dwordx4 v[184:187], v[60:61], off
	global_load_dwordx4 v[226:229], v[60:61], off offset:64
	global_load_dwordx4 v[188:191], v[62:63], off
	global_load_dwordx4 v[230:233], v[62:63], off offset:64
	global_load_dwordx4 v[192:195], v[64:65], off
	global_load_dwordx4 v[234:237], v[64:65], off offset:64
	global_load_dwordx4 v[196:199], v[156:157], off
	global_load_dwordx4 v[238:241], v[156:157], off offset:64
	global_load_dwordx4 v[210:213], v[158:159], off
	global_load_dwordx4 v[242:245], v[158:159], off offset:64
	s_add_u32 s12, s12, 0x80
	s_addc_u32 s13, s13, 0
	s_add_i32 s1, s1, 64
	s_waitcnt vmcnt(33)
; DI void prep_phase(const int wv, const Params& p, int l, LAS unsigned char* lds) {
;     ...
; #pragma unroll 2
;             for (int kk = 0; kk < 16; ++kk) { const int ks = 16 * wave + kk;
;                 const bf16x8 a = *(const bf16x8*)(Arow + (size_t)(ks >> 2) * PWID + (ks & 3) * 32);
; #pragma unroll
;                 for (int nt = 0; nt < 8; ++nt) { const bf16x8 bb = *(const bf16x8*)(Brow + (size_t)nt * 16 * 4096 + ks * 32);
;                     acc[nt] = __builtin_amdgcn_mfma_f32_16x16x32_bf16(a, bb, acc[nt], 0, 0, 0); }
;             }
	v_mfma_f32_16x16x32_bf16 v[16:19], v[82:85], v[92:95], v[16:19]
	s_waitcnt vmcnt(32)
	v_mfma_f32_16x16x32_bf16 v[16:19], v[86:89], v[124:127], v[16:19]
	s_waitcnt vmcnt(31)
	v_mfma_f32_16x16x32_bf16 v[20:23], v[82:85], v[96:99], v[20:23]
	s_waitcnt vmcnt(30)
	v_mfma_f32_16x16x32_bf16 v[20:23], v[86:89], v[128:131], v[20:23]
	s_waitcnt vmcnt(29)
	v_mfma_f32_16x16x32_bf16 v[12:15], v[82:85], v[100:103], v[12:15]
	s_waitcnt vmcnt(28)
	v_mfma_f32_16x16x32_bf16 v[12:15], v[86:89], v[132:135], v[12:15]
	s_waitcnt vmcnt(27)
	v_mfma_f32_16x16x32_bf16 v[8:11], v[82:85], v[104:107], v[8:11]
	s_waitcnt vmcnt(26)
	v_mfma_f32_16x16x32_bf16 v[8:11], v[86:89], v[136:139], v[8:11]
	s_waitcnt vmcnt(25)
	v_mfma_f32_16x16x32_bf16 v[24:27], v[82:85], v[108:111], v[24:27]
	s_waitcnt vmcnt(24)
	v_mfma_f32_16x16x32_bf16 v[24:27], v[86:89], v[140:143], v[24:27]
	s_waitcnt vmcnt(23)
	v_mfma_f32_16x16x32_bf16 v[28:31], v[82:85], v[112:115], v[28:31]
	s_waitcnt vmcnt(22)
	v_mfma_f32_16x16x32_bf16 v[28:31], v[86:89], v[144:147], v[28:31]
	s_waitcnt vmcnt(21)
	v_mfma_f32_16x16x32_bf16 v[0:3], v[82:85], v[116:119], v[0:3]
	s_waitcnt vmcnt(20)
	v_mfma_f32_16x16x32_bf16 v[0:3], v[86:89], v[148:151], v[0:3]
	s_waitcnt vmcnt(19)
	v_mfma_f32_16x16x32_bf16 v[4:7], v[82:85], v[120:123], v[4:7]
	s_waitcnt vmcnt(18)
	v_mfma_f32_16x16x32_bf16 v[4:7], v[86:89], v[152:155], v[4:7]
	s_sub_i32 s17, s1, 32
	v_ashrrev_i32_e32 v50, 2, v80
	s_and_b32 s17, s17, 64
	v_mad_i64_i32 v[50:51], s[18:19], v50, s68, v[46:47]
	s_lshl_b32 s86, s17, 1
	v_lshl_add_u64 v[50:51], v[50:51], 0, s[86:87]
	global_load_dwordx4 v[82:85], v[50:51], off
	v_add_u32_e32 v81, 1, v80
	v_ashrrev_i32_e32 v81, 2, v81
	s_and_b32 s17, s1, 0x60
	s_lshl_b32 s86, s17, 1
	v_mad_i64_i32 v[52:53], s[18:19], v81, s68, v[46:47]
	v_lshl_add_u64 v[52:53], v[52:53], 0, s[86:87]
	global_load_dwordx4 v[86:89], v[52:53], off
	v_add_u32_e32 v80, 2, v80
	v_lshl_add_u64 v[90:91], v[48:49], 0, s[12:13]
	s_mov_b32 s17, 0x5b00000
	v_add_co_u32_e32 v54, vcc, s17, v90
	s_mov_b32 s17, 0x5b20000
	s_nop 0
	v_addc_co_u32_e32 v55, vcc, 0, v91, vcc
	v_add_co_u32_e32 v56, vcc, s17, v90
	s_mov_b32 s17, 0x5b40000
	s_nop 0
	v_addc_co_u32_e32 v57, vcc, 0, v91, vcc
	v_add_co_u32_e32 v58, vcc, s17, v90
	s_mov_b32 s17, 0x5b60000
	s_nop 0
	v_addc_co_u32_e32 v59, vcc, 0, v91, vcc
	v_add_co_u32_e32 v60, vcc, s17, v90
	s_mov_b32 s17, 0x5b80000
	s_nop 0
	v_addc_co_u32_e32 v61, vcc, 0, v91, vcc
	v_add_co_u32_e32 v62, vcc, s17, v90
	s_mov_b32 s17, 0x5ba0000
	s_nop 0
	v_addc_co_u32_e32 v63, vcc, 0, v91, vcc
	v_add_co_u32_e32 v64, vcc, s17, v90
	s_mov_b32 s17, 0x5bc0000
	s_nop 0
	v_addc_co_u32_e32 v65, vcc, 0, v91, vcc
	v_add_co_u32_e32 v156, vcc, s17, v90
	s_mov_b32 s17, 0x5be0000
	s_nop 0
	v_addc_co_u32_e32 v157, vcc, 0, v91, vcc
	v_add_co_u32_e32 v158, vcc, s17, v90
	s_mov_b32 s17, 0x5c00000
	s_nop 0
	v_addc_co_u32_e32 v159, vcc, 0, v91, vcc
	global_load_dwordx4 v[92:95], v[54:55], off
	global_load_dwordx4 v[124:127], v[54:55], off offset:64
	global_load_dwordx4 v[96:99], v[56:57], off
	global_load_dwordx4 v[128:131], v[56:57], off offset:64
	global_load_dwordx4 v[100:103], v[58:59], off
	global_load_dwordx4 v[132:135], v[58:59], off offset:64
	global_load_dwordx4 v[104:107], v[60:61], off
	global_load_dwordx4 v[136:139], v[60:61], off offset:64
	global_load_dwordx4 v[108:111], v[62:63], off
	global_load_dwordx4 v[140:143], v[62:63], off offset:64
	global_load_dwordx4 v[112:115], v[64:65], off
	global_load_dwordx4 v[144:147], v[64:65], off offset:64
	global_load_dwordx4 v[116:119], v[156:157], off
	global_load_dwordx4 v[148:151], v[156:157], off offset:64
	global_load_dwordx4 v[120:123], v[158:159], off
	global_load_dwordx4 v[152:155], v[158:159], off offset:64
	s_add_u32 s12, s12, 0x80
	s_addc_u32 s13, s13, 0
	s_add_i32 s1, s1, 64
	s_waitcnt vmcnt(33)
	v_mfma_f32_16x16x32_bf16 v[16:19], v[162:165], v[172:175], v[16:19]
	s_waitcnt vmcnt(32)
	v_mfma_f32_16x16x32_bf16 v[16:19], v[168:171], v[214:217], v[16:19]
	s_waitcnt vmcnt(31)
	v_mfma_f32_16x16x32_bf16 v[20:23], v[162:165], v[176:179], v[20:23]
	s_waitcnt vmcnt(30)
	v_mfma_f32_16x16x32_bf16 v[20:23], v[168:171], v[218:221], v[20:23]
	s_waitcnt vmcnt(29)
	v_mfma_f32_16x16x32_bf16 v[12:15], v[162:165], v[180:183], v[12:15]
	s_waitcnt vmcnt(28)
	v_mfma_f32_16x16x32_bf16 v[12:15], v[168:171], v[222:225], v[12:15]
	s_waitcnt vmcnt(27)
	v_mfma_f32_16x16x32_bf16 v[8:11], v[162:165], v[184:187], v[8:11]
	s_waitcnt vmcnt(26)
	v_mfma_f32_16x16x32_bf16 v[8:11], v[168:171], v[226:229], v[8:11]
	s_waitcnt vmcnt(25)
	v_mfma_f32_16x16x32_bf16 v[24:27], v[162:165], v[188:191], v[24:27]
	s_waitcnt vmcnt(24)
	v_mfma_f32_16x16x32_bf16 v[24:27], v[168:171], v[230:233], v[24:27]
	s_waitcnt vmcnt(23)
	v_mfma_f32_16x16x32_bf16 v[28:31], v[162:165], v[192:195], v[28:31]
	s_waitcnt vmcnt(22)
	v_mfma_f32_16x16x32_bf16 v[28:31], v[168:171], v[234:237], v[28:31]
	s_waitcnt vmcnt(21)
	v_mfma_f32_16x16x32_bf16 v[0:3], v[162:165], v[196:199], v[0:3]
	s_waitcnt vmcnt(20)
	v_mfma_f32_16x16x32_bf16 v[0:3], v[168:171], v[238:241], v[0:3]
	s_waitcnt vmcnt(19)
	v_mfma_f32_16x16x32_bf16 v[4:7], v[162:165], v[210:213], v[4:7]
	s_waitcnt vmcnt(18)
; DI void prep_phase(const int wv, const Params& p, int l, LAS unsigned char* lds) {
;     ...
; #pragma unroll 2
;             for (int kk = 0; kk < 16; ++kk) { const int ks = 16 * wave + kk;
;                 const bf16x8 a = *(const bf16x8*)(Arow + (size_t)(ks >> 2) * PWID + (ks & 3) * 32);
; #pragma unroll
;                 for (int nt = 0; nt < 8; ++nt) { const bf16x8 bb = *(const bf16x8*)(Brow + (size_t)nt * 16 * 4096 + ks * 32);
;                     acc[nt] = __builtin_amdgcn_mfma_f32_16x16x32_bf16(a, bb, acc[nt], 0, 0, 0); }
;             }
	v_mfma_f32_16x16x32_bf16 v[4:7], v[168:171], v[242:245], v[4:7]
	s_sub_i32 s17, s1, 32
	v_ashrrev_i32_e32 v50, 2, v80
	s_and_b32 s17, s17, 64
	v_mad_i64_i32 v[50:51], s[18:19], v50, s68, v[46:47]
	s_lshl_b32 s86, s17, 1
	v_lshl_add_u64 v[50:51], v[50:51], 0, s[86:87]
	global_load_dwordx4 v[162:165], v[50:51], off
	v_add_u32_e32 v81, 1, v80
	v_ashrrev_i32_e32 v81, 2, v81
	s_and_b32 s17, s1, 0x60
	s_lshl_b32 s86, s17, 1
	v_mad_i64_i32 v[52:53], s[18:19], v81, s68, v[46:47]
	v_lshl_add_u64 v[52:53], v[52:53], 0, s[86:87]
	global_load_dwordx4 v[168:171], v[52:53], off
	v_add_u32_e32 v80, 2, v80
	v_lshl_add_u64 v[90:91], v[48:49], 0, s[12:13]
	s_mov_b32 s17, 0x5b00000
	v_add_co_u32_e32 v54, vcc, s17, v90
	s_mov_b32 s17, 0x5b20000
	s_nop 0
	v_addc_co_u32_e32 v55, vcc, 0, v91, vcc
	v_add_co_u32_e32 v56, vcc, s17, v90
	s_mov_b32 s17, 0x5b40000
	s_nop 0
	v_addc_co_u32_e32 v57, vcc, 0, v91, vcc
	v_add_co_u32_e32 v58, vcc, s17, v90
	s_mov_b32 s17, 0x5b60000
	s_nop 0
	v_addc_co_u32_e32 v59, vcc, 0, v91, vcc
	v_add_co_u32_e32 v60, vcc, s17, v90
	s_mov_b32 s17, 0x5b80000
	s_nop 0
	v_addc_co_u32_e32 v61, vcc, 0, v91, vcc
	v_add_co_u32_e32 v62, vcc, s17, v90
	s_mov_b32 s17, 0x5ba0000
	s_nop 0
	v_addc_co_u32_e32 v63, vcc, 0, v91, vcc
	v_add_co_u32_e32 v64, vcc, s17, v90
	s_mov_b32 s17, 0x5bc0000
	s_nop 0
	v_addc_co_u32_e32 v65, vcc, 0, v91, vcc
	v_add_co_u32_e32 v156, vcc, s17, v90
	s_mov_b32 s17, 0x5be0000
	s_nop 0
	v_addc_co_u32_e32 v157, vcc, 0, v91, vcc
	v_add_co_u32_e32 v158, vcc, s17, v90
	s_mov_b32 s17, 0x5c00000
	s_nop 0
	v_addc_co_u32_e32 v159, vcc, 0, v91, vcc
	global_load_dwordx4 v[172:175], v[54:55], off
	global_load_dwordx4 v[214:217], v[54:55], off offset:64
	global_load_dwordx4 v[176:179], v[56:57], off
	global_load_dwordx4 v[218:221], v[56:57], off offset:64
	global_load_dwordx4 v[180:183], v[58:59], off
	global_load_dwordx4 v[222:225], v[58:59], off offset:64
	global_load_dwordx4 v[184:187], v[60:61], off
	global_load_dwordx4 v[226:229], v[60:61], off offset:64
	global_load_dwordx4 v[188:191], v[62:63], off
	global_load_dwordx4 v[230:233], v[62:63], off offset:64
	global_load_dwordx4 v[192:195], v[64:65], off
	global_load_dwordx4 v[234:237], v[64:65], off offset:64
	global_load_dwordx4 v[196:199], v[156:157], off
	global_load_dwordx4 v[238:241], v[156:157], off offset:64
	global_load_dwordx4 v[210:213], v[158:159], off
	global_load_dwordx4 v[242:245], v[158:159], off offset:64
	s_add_u32 s12, s12, 0x80
	s_addc_u32 s13, s13, 0
	s_add_i32 s1, s1, 64
	s_waitcnt vmcnt(33)
	v_mfma_f32_16x16x32_bf16 v[16:19], v[82:85], v[92:95], v[16:19]
	s_waitcnt vmcnt(32)
	v_mfma_f32_16x16x32_bf16 v[16:19], v[86:89], v[124:127], v[16:19]
	s_waitcnt vmcnt(31)
	v_mfma_f32_16x16x32_bf16 v[20:23], v[82:85], v[96:99], v[20:23]
	s_waitcnt vmcnt(30)
	v_mfma_f32_16x16x32_bf16 v[20:23], v[86:89], v[128:131], v[20:23]
	s_waitcnt vmcnt(29)
	v_mfma_f32_16x16x32_bf16 v[12:15], v[82:85], v[100:103], v[12:15]
	s_waitcnt vmcnt(28)
	v_mfma_f32_16x16x32_bf16 v[12:15], v[86:89], v[132:135], v[12:15]
	s_waitcnt vmcnt(27)
	v_mfma_f32_16x16x32_bf16 v[8:11], v[82:85], v[104:107], v[8:11]
	s_waitcnt vmcnt(26)
	v_mfma_f32_16x16x32_bf16 v[8:11], v[86:89], v[136:139], v[8:11]
	s_waitcnt vmcnt(25)
	v_mfma_f32_16x16x32_bf16 v[24:27], v[82:85], v[108:111], v[24:27]
	s_waitcnt vmcnt(24)
	v_mfma_f32_16x16x32_bf16 v[24:27], v[86:89], v[140:143], v[24:27]
	s_waitcnt vmcnt(23)
	v_mfma_f32_16x16x32_bf16 v[28:31], v[82:85], v[112:115], v[28:31]
	s_waitcnt vmcnt(22)
	v_mfma_f32_16x16x32_bf16 v[28:31], v[86:89], v[144:147], v[28:31]
	s_waitcnt vmcnt(21)
	v_mfma_f32_16x16x32_bf16 v[0:3], v[82:85], v[116:119], v[0:3]
	s_waitcnt vmcnt(20)
	v_mfma_f32_16x16x32_bf16 v[0:3], v[86:89], v[148:151], v[0:3]
	s_waitcnt vmcnt(19)
	v_mfma_f32_16x16x32_bf16 v[4:7], v[82:85], v[120:123], v[4:7]
	s_waitcnt vmcnt(18)
	v_mfma_f32_16x16x32_bf16 v[4:7], v[86:89], v[152:155], v[4:7]
	s_sub_i32 s17, s1, 32
	v_ashrrev_i32_e32 v50, 2, v80
	s_and_b32 s17, s17, 64
	v_mad_i64_i32 v[50:51], s[18:19], v50, s68, v[46:47]
	s_lshl_b32 s86, s17, 1
	v_lshl_add_u64 v[50:51], v[50:51], 0, s[86:87]
	global_load_dwordx4 v[82:85], v[50:51], off
	v_add_u32_e32 v81, 1, v80
	v_ashrrev_i32_e32 v81, 2, v81
	s_and_b32 s17, s1, 0x60
	s_lshl_b32 s86, s17, 1
	v_mad_i64_i32 v[52:53], s[18:19], v81, s68, v[46:47]
	v_lshl_add_u64 v[52:53], v[52:53], 0, s[86:87]
	global_load_dwordx4 v[86:89], v[52:53], off
	v_add_u32_e32 v80, 2, v80
	v_lshl_add_u64 v[90:91], v[48:49], 0, s[12:13]
	s_mov_b32 s17, 0x5b00000
	v_add_co_u32_e32 v54, vcc, s17, v90
	s_mov_b32 s17, 0x5b20000
	s_nop 0
	v_addc_co_u32_e32 v55, vcc, 0, v91, vcc
	v_add_co_u32_e32 v56, vcc, s17, v90
	s_mov_b32 s17, 0x5b40000
	s_nop 0
	v_addc_co_u32_e32 v57, vcc, 0, v91, vcc
	v_add_co_u32_e32 v58, vcc, s17, v90
	s_mov_b32 s17, 0x5b60000
	s_nop 0
	v_addc_co_u32_e32 v59, vcc, 0, v91, vcc
	v_add_co_u32_e32 v60, vcc, s17, v90
	s_mov_b32 s17, 0x5b80000
	s_nop 0
	v_addc_co_u32_e32 v61, vcc, 0, v91, vcc
	v_add_co_u32_e32 v62, vcc, s17, v90
	s_mov_b32 s17, 0x5ba0000
	s_nop 0
	v_addc_co_u32_e32 v63, vcc, 0, v91, vcc
	v_add_co_u32_e32 v64, vcc, s17, v90
	s_mov_b32 s17, 0x5bc0000
	s_nop 0
	v_addc_co_u32_e32 v65, vcc, 0, v91, vcc
	v_add_co_u32_e32 v156, vcc, s17, v90
	s_mov_b32 s17, 0x5be0000
	s_nop 0
	v_addc_co_u32_e32 v157, vcc, 0, v91, vcc
	v_add_co_u32_e32 v158, vcc, s17, v90
	s_mov_b32 s17, 0x5c00000
	s_nop 0
	v_addc_co_u32_e32 v159, vcc, 0, v91, vcc
	global_load_dwordx4 v[92:95], v[54:55], off
	global_load_dwordx4 v[124:127], v[54:55], off offset:64
	global_load_dwordx4 v[96:99], v[56:57], off
	global_load_dwordx4 v[128:131], v[56:57], off offset:64
	global_load_dwordx4 v[100:103], v[58:59], off
	global_load_dwordx4 v[132:135], v[58:59], off offset:64
	global_load_dwordx4 v[104:107], v[60:61], off
	global_load_dwordx4 v[136:139], v[60:61], off offset:64
	global_load_dwordx4 v[108:111], v[62:63], off
	global_load_dwordx4 v[140:143], v[62:63], off offset:64
	global_load_dwordx4 v[112:115], v[64:65], off
	global_load_dwordx4 v[144:147], v[64:65], off offset:64
	global_load_dwordx4 v[116:119], v[156:157], off
	global_load_dwordx4 v[148:151], v[156:157], off offset:64
	global_load_dwordx4 v[120:123], v[158:159], off
	global_load_dwordx4 v[152:155], v[158:159], off offset:64
	s_add_u32 s12, s12, 0x80
	s_addc_u32 s13, s13, 0
	s_add_i32 s1, s1, 64
	s_waitcnt vmcnt(33)
; #define LAS __attribute__((address_space(3)))
; DI unsigned pk2(float lo, float hi) { f32x2 v = {lo, hi}; bf16x2n b = __builtin_convertvector(v, bf16x2n); return __builtin_bit_cast(unsigned, b); }
; DI float silu_f(float x) { return x * fast_rcp(1.f + fast_exp2(-1.44269504f * x)); }
; DI void prep_phase(const int wv, const Params& p, int l, LAS unsigned char* lds) {
;     ...
; #pragma unroll 2
;             for (int kk = 0; kk < 16; ++kk) { const int ks = 16 * wave + kk;
;                 const bf16x8 a = *(const bf16x8*)(Arow + (size_t)(ks >> 2) * PWID + (ks & 3) * 32);
; #pragma unroll
;                 for (int nt = 0; nt < 8; ++nt) { const bf16x8 bb = *(const bf16x8*)(Brow + (size_t)nt * 16 * 4096 + ks * 32);
;                     acc[nt] = __builtin_amdgcn_mfma_f32_16x16x32_bf16(a, bb, acc[nt], 0, 0, 0); }
;             }
;     ...
;             { const int row = tid >> 5, n4 = (tid & 31) * 4; f32x4 s = *(const f32x4*)(bias1 + kv * 128 + n4);
; #pragma unroll
;               for (int w = 0; w < 8; ++w) s += *(const LAS f32x4*)(part + (w * 16 + row) * 128 + n4);
;               u32x2 hv; hv.x = pk2(silu_f(s.x), silu_f(s.y)); hv.y = pk2(silu_f(s.z), silu_f(s.w));
;               *(LAS u32x2*)(Hs + row * 136 + n4) = hv; }
;             __syncthreads();
;             f32x4 acc2 = {0.f, 0.f, 0.f, 0.f};
; #pragma unroll
;             for (int ks = 0; ks < 4; ++ks) {
;                 const bf16x8 a = *(const LAS bf16x8*)(Hs + r16 * 136 + ks * 32 + 8 * kq);
;                 const bf16x8 bb = *(const bf16x8*)(W2t + (size_t)(16 * wave + r16) * 128 + ks * 32 + 8 * kq);
;                 acc2 = __builtin_amdgcn_mfma_f32_16x16x32_bf16(a, bb, acc2, 0, 0, 0);
;             }
;             const int n = 16 * wave + r16;
;             if (kv == 0) {
;                 float ss[4];
; #pragma unroll
;                 for (int i = 0; i < 4; ++i) { float s = acc2[i] * acc2[i]; s += __shfl_xor(s, 1); s += __shfl_xor(s, 2); s += __shfl_xor(s, 4); s += __shfl_xor(s, 8); ss[i] = s; }
;                 if (r16 == 0) {
; #pragma unroll
;                     for (int i = 0; i < 4; ++i) red[wave * 16 + 4 * kq + i] = ss[i]; }
;                 __syncthreads();
;                 const float gn = p.k_gain[(l * 3 + 0) * 128 + n];
	v_mfma_f32_16x16x32_bf16 v[16:19], v[162:165], v[172:175], v[16:19]
	s_waitcnt vmcnt(32)
	v_mfma_f32_16x16x32_bf16 v[16:19], v[168:171], v[214:217], v[16:19]
	s_waitcnt vmcnt(31)
	v_mfma_f32_16x16x32_bf16 v[20:23], v[162:165], v[176:179], v[20:23]
	s_waitcnt vmcnt(30)
	v_mfma_f32_16x16x32_bf16 v[20:23], v[168:171], v[218:221], v[20:23]
	s_waitcnt vmcnt(29)
	v_mfma_f32_16x16x32_bf16 v[12:15], v[162:165], v[180:183], v[12:15]
	s_waitcnt vmcnt(28)
	v_mfma_f32_16x16x32_bf16 v[12:15], v[168:171], v[222:225], v[12:15]
	s_waitcnt vmcnt(27)
	v_mfma_f32_16x16x32_bf16 v[8:11], v[162:165], v[184:187], v[8:11]
	s_waitcnt vmcnt(26)
	v_mfma_f32_16x16x32_bf16 v[8:11], v[168:171], v[226:229], v[8:11]
	s_waitcnt vmcnt(25)
	v_mfma_f32_16x16x32_bf16 v[24:27], v[162:165], v[188:191], v[24:27]
	s_waitcnt vmcnt(24)
	v_mfma_f32_16x16x32_bf16 v[24:27], v[168:171], v[230:233], v[24:27]
	s_waitcnt vmcnt(23)
	v_mfma_f32_16x16x32_bf16 v[28:31], v[162:165], v[192:195], v[28:31]
	s_waitcnt vmcnt(22)
	v_mfma_f32_16x16x32_bf16 v[28:31], v[168:171], v[234:237], v[28:31]
	s_waitcnt vmcnt(21)
	v_mfma_f32_16x16x32_bf16 v[0:3], v[162:165], v[196:199], v[0:3]
	s_waitcnt vmcnt(20)
	v_mfma_f32_16x16x32_bf16 v[0:3], v[168:171], v[238:241], v[0:3]
	s_waitcnt vmcnt(19)
	v_mfma_f32_16x16x32_bf16 v[4:7], v[162:165], v[210:213], v[4:7]
	s_waitcnt vmcnt(18)
	v_mfma_f32_16x16x32_bf16 v[4:7], v[168:171], v[242:245], v[4:7]
	s_sub_i32 s17, s1, 32
	v_ashrrev_i32_e32 v50, 2, v80
	s_and_b32 s17, s17, 64
	v_mad_i64_i32 v[50:51], s[18:19], v50, s68, v[46:47]
	s_lshl_b32 s86, s17, 1
	v_lshl_add_u64 v[50:51], v[50:51], 0, s[86:87]
	global_load_dwordx4 v[162:165], v[50:51], off
	v_add_u32_e32 v81, 1, v80
	v_ashrrev_i32_e32 v81, 2, v81
	s_and_b32 s17, s1, 0x60
	s_lshl_b32 s86, s17, 1
	v_mad_i64_i32 v[52:53], s[18:19], v81, s68, v[46:47]
	v_lshl_add_u64 v[52:53], v[52:53], 0, s[86:87]
	global_load_dwordx4 v[168:171], v[52:53], off
	v_add_u32_e32 v80, 2, v80
	v_lshl_add_u64 v[90:91], v[48:49], 0, s[12:13]
	s_mov_b32 s17, 0x5b00000
	v_add_co_u32_e32 v54, vcc, s17, v90
	s_mov_b32 s17, 0x5b20000
	s_nop 0
	v_addc_co_u32_e32 v55, vcc, 0, v91, vcc
	v_add_co_u32_e32 v56, vcc, s17, v90
	s_mov_b32 s17, 0x5b40000
	s_nop 0
	v_addc_co_u32_e32 v57, vcc, 0, v91, vcc
	v_add_co_u32_e32 v58, vcc, s17, v90
	s_mov_b32 s17, 0x5b60000
	s_nop 0
	v_addc_co_u32_e32 v59, vcc, 0, v91, vcc
	v_add_co_u32_e32 v60, vcc, s17, v90
	s_mov_b32 s17, 0x5b80000
	s_nop 0
	v_addc_co_u32_e32 v61, vcc, 0, v91, vcc
	v_add_co_u32_e32 v62, vcc, s17, v90
	s_mov_b32 s17, 0x5ba0000
	s_nop 0
	v_addc_co_u32_e32 v63, vcc, 0, v91, vcc
	v_add_co_u32_e32 v64, vcc, s17, v90
	s_mov_b32 s17, 0x5bc0000
	s_nop 0
	v_addc_co_u32_e32 v65, vcc, 0, v91, vcc
	v_add_co_u32_e32 v156, vcc, s17, v90
	s_mov_b32 s17, 0x5be0000
	s_nop 0
	v_addc_co_u32_e32 v157, vcc, 0, v91, vcc
	v_add_co_u32_e32 v158, vcc, s17, v90
	s_mov_b32 s17, 0x5c00000
	s_nop 0
	v_addc_co_u32_e32 v159, vcc, 0, v91, vcc
	global_load_dwordx4 v[172:175], v[54:55], off
	global_load_dwordx4 v[214:217], v[54:55], off offset:64
	global_load_dwordx4 v[176:179], v[56:57], off
	global_load_dwordx4 v[218:221], v[56:57], off offset:64
	global_load_dwordx4 v[180:183], v[58:59], off
	global_load_dwordx4 v[222:225], v[58:59], off offset:64
	global_load_dwordx4 v[184:187], v[60:61], off
	global_load_dwordx4 v[226:229], v[60:61], off offset:64
	global_load_dwordx4 v[188:191], v[62:63], off
	global_load_dwordx4 v[230:233], v[62:63], off offset:64
	global_load_dwordx4 v[192:195], v[64:65], off
	global_load_dwordx4 v[234:237], v[64:65], off offset:64
	global_load_dwordx4 v[196:199], v[156:157], off
	global_load_dwordx4 v[238:241], v[156:157], off offset:64
	global_load_dwordx4 v[210:213], v[158:159], off
	global_load_dwordx4 v[242:245], v[158:159], off offset:64
	s_add_u32 s12, s12, 0x80
	s_addc_u32 s13, s13, 0
	s_add_i32 s1, s1, 64
	s_waitcnt vmcnt(33)
	v_mfma_f32_16x16x32_bf16 v[16:19], v[82:85], v[92:95], v[16:19]
	s_waitcnt vmcnt(32)
	v_mfma_f32_16x16x32_bf16 v[16:19], v[86:89], v[124:127], v[16:19]
	s_waitcnt vmcnt(31)
	v_mfma_f32_16x16x32_bf16 v[20:23], v[82:85], v[96:99], v[20:23]
	s_waitcnt vmcnt(30)
	v_mfma_f32_16x16x32_bf16 v[20:23], v[86:89], v[128:131], v[20:23]
	s_waitcnt vmcnt(29)
	v_mfma_f32_16x16x32_bf16 v[12:15], v[82:85], v[100:103], v[12:15]
	s_waitcnt vmcnt(28)
	v_mfma_f32_16x16x32_bf16 v[12:15], v[86:89], v[132:135], v[12:15]
	s_waitcnt vmcnt(27)
	v_mfma_f32_16x16x32_bf16 v[8:11], v[82:85], v[104:107], v[8:11]
	s_waitcnt vmcnt(26)
	v_mfma_f32_16x16x32_bf16 v[8:11], v[86:89], v[136:139], v[8:11]
	s_waitcnt vmcnt(25)
	v_mfma_f32_16x16x32_bf16 v[24:27], v[82:85], v[108:111], v[24:27]
	s_waitcnt vmcnt(24)
	v_mfma_f32_16x16x32_bf16 v[24:27], v[86:89], v[140:143], v[24:27]
	s_waitcnt vmcnt(23)
	v_mfma_f32_16x16x32_bf16 v[28:31], v[82:85], v[112:115], v[28:31]
	s_waitcnt vmcnt(22)
	v_mfma_f32_16x16x32_bf16 v[28:31], v[86:89], v[144:147], v[28:31]
	s_waitcnt vmcnt(21)
	v_mfma_f32_16x16x32_bf16 v[0:3], v[82:85], v[116:119], v[0:3]
	s_waitcnt vmcnt(20)
	v_mfma_f32_16x16x32_bf16 v[0:3], v[86:89], v[148:151], v[0:3]
	s_waitcnt vmcnt(19)
	v_mfma_f32_16x16x32_bf16 v[4:7], v[82:85], v[120:123], v[4:7]
	s_waitcnt vmcnt(18)
	v_mfma_f32_16x16x32_bf16 v[4:7], v[86:89], v[152:155], v[4:7]
	s_and_b32 s12, s14, 0xffffff80
	s_ashr_i32 s13, s12, 31
	v_lshl_add_u64 v[112:113], s[12:13], 2, v[34:35]
	global_load_dwordx4 v[92:95], v[112:113], off
	s_lshl_b64 s[18:19], s[10:11], 15
	v_lshl_add_u64 v[114:115], v[38:39], 0, s[18:19]
	global_load_dwordx4 v[96:99], v[114:115], off
	global_load_dwordx4 v[100:103], v[114:115], off offset:64
	global_load_dwordx4 v[104:107], v[114:115], off offset:128
	global_load_dwordx4 v[108:111], v[114:115], off offset:192
	global_load_dword v116, v[42:43], off
	s_waitcnt vmcnt(21)
; DI void prep_phase(const int wv, const Params& p, int l, LAS unsigned char* lds) {
;     ...
;                 for (int nt = 0; nt < 8; ++nt) { const bf16x8 bb = *(const bf16x8*)(Brow + (size_t)nt * 16 * 4096 + ks * 32);
;                     acc[nt] = __builtin_amdgcn_mfma_f32_16x16x32_bf16(a, bb, acc[nt], 0, 0, 0); }
;             }
;             __syncthreads();
; #pragma unroll
;             for (int nt = 0; nt < 8; ++nt)
; #pragma unroll
;                 for (int i = 0; i < 4; ++i) part[(wave * 16 + 4 * kq + i) * 128 + 16 * nt + r16] = acc[nt][i];
;             __syncthreads();
;             { const int row = tid >> 5, n4 = (tid & 31) * 4; f32x4 s = *(const f32x4*)(bias1 + kv * 128 + n4);
; #pragma unroll
;               for (int w = 0; w < 8; ++w) s += *(const LAS f32x4*)(part + (w * 16 + row) * 128 + n4);
;               u32x2 hv; hv.x = pk2(silu_f(s.x), silu_f(s.y)); hv.y = pk2(silu_f(s.z), silu_f(s.w));
;               *(LAS u32x2*)(Hs + row * 136 + n4) = hv; }
;             __syncthreads();
;             f32x4 acc2 = {0.f, 0.f, 0.f, 0.f};
; #pragma unroll
;             for (int ks = 0; ks < 4; ++ks) {
;                 const bf16x8 a = *(const LAS bf16x8*)(Hs + r16 * 136 + ks * 32 + 8 * kq);
;                 const bf16x8 bb = *(const bf16x8*)(W2t + (size_t)(16 * wave + r16) * 128 + ks * 32 + 8 * kq);
;                 acc2 = __builtin_amdgcn_mfma_f32_16x16x32_bf16(a, bb, acc2, 0, 0, 0);
;             }
;             const int n = 16 * wave + r16;
;             if (kv == 0) {
;                 float ss[4];
; #pragma unroll
;                 for (int i = 0; i < 4; ++i) { float s = acc2[i] * acc2[i]; s += __shfl_xor(s, 1); s += __shfl_xor(s, 2); s += __shfl_xor(s, 4); s += __shfl_xor(s, 8); ss[i] = s; }
;                 if (r16 == 0) {
; #pragma unroll
;                     for (int i = 0; i < 4; ++i) red[wave * 16 + 4 * kq + i] = ss[i]; }
;                 __syncthreads();
;                 const float gn = p.k_gain[(l * 3 + 0) * 128 + n];
; #pragma unroll
;                 for (int i = 0; i < 4; ++i) { const int row = 4 * kq + i; float s = 0.f;
; #pragma unroll
;                     for (int w = 0; w < 8; ++w) s += red[w * 16 + row];
;                     const float rstd = rsqrtf(s * (1.f / 128.f) + 1e-6f); const int c = c0 + row;
;                     const float v = (c < 255) ? acc2[i] * rstd * gn : 0.f;
	v_mfma_f32_16x16x32_bf16 v[16:19], v[162:165], v[172:175], v[16:19]
	s_waitcnt vmcnt(20)
	v_mfma_f32_16x16x32_bf16 v[16:19], v[168:171], v[214:217], v[16:19]
	s_waitcnt vmcnt(19)
	v_mfma_f32_16x16x32_bf16 v[20:23], v[162:165], v[176:179], v[20:23]
	s_waitcnt vmcnt(18)
	v_mfma_f32_16x16x32_bf16 v[20:23], v[168:171], v[218:221], v[20:23]
	s_waitcnt vmcnt(17)
	v_mfma_f32_16x16x32_bf16 v[12:15], v[162:165], v[180:183], v[12:15]
	s_waitcnt vmcnt(16)
	v_mfma_f32_16x16x32_bf16 v[12:15], v[168:171], v[222:225], v[12:15]
	s_waitcnt vmcnt(15)
	v_mfma_f32_16x16x32_bf16 v[8:11], v[162:165], v[184:187], v[8:11]
	s_waitcnt vmcnt(14)
	v_mfma_f32_16x16x32_bf16 v[8:11], v[168:171], v[226:229], v[8:11]
	s_waitcnt vmcnt(13)
	v_mfma_f32_16x16x32_bf16 v[24:27], v[162:165], v[188:191], v[24:27]
	s_waitcnt vmcnt(12)
	v_mfma_f32_16x16x32_bf16 v[24:27], v[168:171], v[230:233], v[24:27]
	s_waitcnt vmcnt(11)
	v_mfma_f32_16x16x32_bf16 v[28:31], v[162:165], v[192:195], v[28:31]
	s_waitcnt vmcnt(10)
	v_mfma_f32_16x16x32_bf16 v[28:31], v[168:171], v[234:237], v[28:31]
	s_waitcnt vmcnt(9)
	v_mfma_f32_16x16x32_bf16 v[0:3], v[162:165], v[196:199], v[0:3]
	s_waitcnt vmcnt(8)
	v_mfma_f32_16x16x32_bf16 v[0:3], v[168:171], v[238:241], v[0:3]
	s_waitcnt vmcnt(7)
	v_mfma_f32_16x16x32_bf16 v[4:7], v[162:165], v[210:213], v[4:7]
	s_waitcnt vmcnt(6)
	v_mfma_f32_16x16x32_bf16 v[4:7], v[168:171], v[242:245], v[4:7]
	v_add_u32_e32 v46, 0x4000, v78
	s_and_b32 s12, s14, 0xffffff80
	s_waitcnt lgkmcnt(0)
	s_barrier
	ds_write2_b32 v46, v16, v20 offset1:16
	ds_write2_b32 v46, v17, v21 offset0:128 offset1:144
	v_add_u32_e32 v16, 0x4400, v78
	s_ashr_i32 s13, s12, 31
	ds_write2_b32 v16, v18, v22 offset1:16
	ds_write2_b32 v16, v19, v23 offset0:128 offset1:144
	ds_write2_b32 v46, v12, v8 offset0:32 offset1:48
	ds_write2_b32 v46, v13, v9 offset0:160 offset1:176
	ds_write2_b32 v16, v14, v10 offset0:32 offset1:48
	ds_write2_b32 v16, v15, v11 offset0:160 offset1:176
	ds_write2_b32 v46, v24, v28 offset0:64 offset1:80
	ds_write2_b32 v46, v25, v29 offset0:192 offset1:208
	ds_write2_b32 v16, v26, v30 offset0:64 offset1:80
	ds_write2_b32 v16, v27, v31 offset0:192 offset1:208
	ds_write2_b32 v46, v0, v4 offset0:96 offset1:112
	ds_write2_b32 v46, v1, v5 offset0:224 offset1:240
	ds_write2_b32 v16, v2, v6 offset0:96 offset1:112
	ds_write2_b32 v16, v3, v7 offset0:224 offset1:240
	v_lshl_add_u64 v[0:1], s[12:13], 2, v[34:35]
	s_waitcnt lgkmcnt(0)
	s_barrier
	s_nop 0
	ds_read_b128 v[4:7], v70 offset:16384
	s_lshl_b64 s[10:11], s[10:11], 15
	v_lshl_add_u64 v[12:13], v[38:39], 0, s[10:11]
	s_mov_b64 s[10:11], -1
	s_and_b64 vcc, exec, s[8:9]
	s_waitcnt vmcnt(0) lgkmcnt(0)
	v_pk_add_f32 v[6:7], v[94:95], v[6:7]
	v_pk_add_f32 v[4:5], v[92:93], v[4:5]
	ds_read_b128 v[0:3], v70 offset:24576
	s_waitcnt lgkmcnt(0)
	v_pk_add_f32 v[6:7], v[6:7], v[2:3]
	v_pk_add_f32 v[4:5], v[4:5], v[0:1]
	ds_read_b128 v[0:3], v70 offset:32768
	s_waitcnt lgkmcnt(0)
	v_pk_add_f32 v[6:7], v[6:7], v[2:3]
	v_pk_add_f32 v[4:5], v[4:5], v[0:1]
	ds_read_b128 v[0:3], v70 offset:40960
	s_waitcnt lgkmcnt(0)
	v_pk_add_f32 v[6:7], v[6:7], v[2:3]
	v_pk_add_f32 v[4:5], v[4:5], v[0:1]
	ds_read_b128 v[0:3], v70 offset:49152
	s_waitcnt lgkmcnt(0)
	v_pk_add_f32 v[6:7], v[6:7], v[2:3]
	v_pk_add_f32 v[4:5], v[4:5], v[0:1]
	ds_read_b128 v[0:3], v70 offset:57344
	s_waitcnt lgkmcnt(0)
	v_pk_add_f32 v[6:7], v[6:7], v[2:3]
	v_pk_add_f32 v[4:5], v[4:5], v[0:1]
	ds_read_b128 v[0:3], v71 offset:49152
	s_waitcnt lgkmcnt(0)
	v_pk_add_f32 v[6:7], v[6:7], v[2:3]
	v_pk_add_f32 v[4:5], v[4:5], v[0:1]
	ds_read_b128 v[0:3], v71 offset:57344
	s_waitcnt lgkmcnt(0)
	v_pk_add_f32 v[0:1], v[4:5], v[0:1]
	s_nop 0
	v_mul_f32_e32 v4, 0xbfb8aa3b, v0
	v_mul_f32_e32 v5, 0xbfb8aa3b, v1
	v_exp_f32_e32 v4, v4
	v_exp_f32_e32 v5, v5
	v_pk_add_f32 v[2:3], v[6:7], v[2:3]
	v_add_f32_e32 v4, 1.0, v4
	v_add_f32_e32 v5, 1.0, v5
	v_rcp_f32_e32 v4, v4
	v_rcp_f32_e32 v5, v5
	s_nop 0
	v_pk_mul_f32 v[0:1], v[0:1], v[4:5]
	s_nop 0
	v_cvt_pk_bf16_f32 v0, v0, v1
	v_mul_f32_e32 v1, 0xbfb8aa3b, v2
	v_exp_f32_e32 v1, v1
	s_nop 0
	v_add_f32_e32 v1, 1.0, v1
	v_rcp_f32_e32 v4, v1
	v_mul_f32_e32 v1, 0xbfb8aa3b, v3
	v_exp_f32_e32 v1, v1
	s_nop 0
	v_add_f32_e32 v1, 1.0, v1
	v_rcp_f32_e32 v5, v1
	s_nop 0
	v_pk_mul_f32 v[2:3], v[2:3], v[4:5]
	s_nop 0
	v_cvt_pk_bf16_f32 v1, v2, v3
	ds_write_b64 v72, v[0:1]
	s_waitcnt lgkmcnt(0)
	s_barrier
	s_nop 0
	s_nop 0
	ds_read_b128 v[0:3], v73
	s_waitcnt vmcnt(1) lgkmcnt(0)
	v_mfma_f32_16x16x32_bf16 v[0:3], v[0:3], v[96:99], 0
	ds_read_b128 v[4:7], v73 offset:64
	s_waitcnt vmcnt(0) lgkmcnt(0)
	v_mfma_f32_16x16x32_bf16 v[0:3], v[4:7], v[100:103], v[0:3]
	s_nop 0
	ds_read_b128 v[4:7], v73 offset:128
	s_waitcnt vmcnt(0) lgkmcnt(0)
	v_mfma_f32_16x16x32_bf16 v[0:3], v[4:7], v[104:107], v[0:3]
	s_nop 0
	ds_read_b128 v[4:7], v73 offset:192
	v_or_b32_e32 v12, s15, v32
	s_waitcnt vmcnt(0) lgkmcnt(0)
	v_mfma_f32_16x16x32_bf16 v[0:3], v[4:7], v[108:111], v[0:3]
	s_cbranch_vccz .LBB0_365
	s_movk_i32 s1, 0xfc
	v_cmp_ne_u32_e32 vcc, s1, v12
	v_lshl_add_u64 v[6:7], s[6:7], 0, v[36:37]
	s_lshl_b32 s1, s16, 17
	v_readlane_b32 s6, v253, 63
	s_add_u32 s6, s6, s1
	v_readlane_b32 s1, v254, 0
	v_lshlrev_b64 v[6:7], 9, v[6:7]
	s_addc_u32 s7, s1, 0
	v_lshl_add_u64 v[6:7], s[6:7], 0, v[6:7]
	s_lshl_b32 s86, s15, 1
	v_cndmask_b32_e32 v5, 0, v3, vcc
	v_lshl_add_u64 v[6:7], v[6:7], 0, s[86:87]
	v_lshlrev_b32_e32 v8, 1, v32
	v_mov_b32_e32 v9, v161
	v_cvt_pk_bf16_f32 v4, v0, v1
	v_cvt_pk_bf16_f32 v5, v2, v5
	v_lshl_add_u64 v[6:7], v[6:7], 0, v[8:9]
	global_store_dwordx2 v[6:7], v[4:5], off
	s_cbranch_execnz .LBB0_360
	s_branch .LBB0_366
